# dense main loop: -m read straight from v[114:129] by the first QK^T MFMA pair, the 8 per-tile v_mov_b64 copies removed
# baseline (speedup 1.0000x reference)
; #define SBAR() __builtin_amdgcn_sched_barrier(0)
; #define KRD(f, d0, kb) asm volatile("ds_read_b128 %0, %2 offset:%3\n\tds_read_b128 %1, %2 offset:%4" : "=&v"(f.a), "=&v"(f.b) : "v"((kb) + koff[(d0) & 3]), "i"(((d0) >> 2) * 128), "i"(((d0) >> 2) * 128 + 8192) : "memory")
; #define QMM(f, d0) do { pA0 = __builtin_amdgcn_mfma_f32_32x32x16_bf16(f.a, qr[d0], pA0, 0, 0, 0); pA1 = __builtin_amdgcn_mfma_f32_32x32x16_bf16(f.b, qr[d0], pA1, 0, 0, 0); } while (0)
; #define LW(n) do { asm volatile("s_waitcnt lgkmcnt(" #n ")" ::: "memory"); SBAR(); } while (0)
;     ...
;         LW(10); pA0 = __builtin_amdgcn_mfma_f32_32x32x16_bf16(k0_.a, qr[0], negm, 0, 0, 0); pA1 = __builtin_amdgcn_mfma_f32_32x32x16_bf16(k0_.b, qr[0], negm, 0, 0, 0); SBAR(); KRD(k0_, 2, kb_);
;     ...
;         pA0 = f32x16{}; pA1 = f32x16{};
;         LW(10); QMM(k0_, 0); SBAR(); KRD(k0_, 2, kb_);
;     ...
;         LW(10); QMM(k1_, 1); SBAR(); KRD(k1_, 3, kb_);
;         LW(4);  pv_mm(o[0], fa_, pa0, pa1, pa2, pa3); SBAR(); pv_rd<1>(fb_, vb_);
;         LW(10); QMM(k0_, 2); SBAR(); KRD(k0_, 4, kb_);
;         LW(10); QMM(k1_, 3); SBAR(); KRD(k1_, 5, kb_);
;         LW(4);  pv_mm(o[1], fb_, pa0, pa1, pa2, pa3); SBAR(); pv_rd<2>(fa_, vb_);
;         LW(10); QMM(k0_, 4); SBAR(); KRD(k0_, 6, kb_);
;         LW(10); QMM(k1_, 5); SBAR(); KRD(k1_, 7, kb_);
;         LW(4);  pv_mm(o[2], fa_, pa0, pa1, pa2, pa3); SBAR(); pv_rd<3>(fb_, vb_);
;         LW(10); QMM(k0_, 6); SBAR();
;         LW(8);  QMM(k1_, 7); SBAR();
;         LW(0);  pv_mm(o[3], fb_, pa0, pa1, pa2, pa3);
.LBB0_69:
	s_waitcnt lgkmcnt(10)
	v_mfma_f32_32x32x16_bf16 v[98:113], v[82:85], v[158:161], v[114:129]
	v_mfma_f32_32x32x16_bf16 v[82:97], v[202:205], v[158:161], v[114:129]
	v_add_u32_e32 v217, s87, v237
	ds_read_b128 v[202:205], v217 offset:0
	ds_read_b128 v[250:253], v217 offset:0x2000
	s_waitcnt lgkmcnt(10)
	v_mfma_f32_32x32x16_bf16 v[98:113], v[198:201], v[154:157], v[98:113]
	v_mfma_f32_32x32x16_bf16 v[82:97], v[194:197], v[154:157], v[82:97]
	v_add_u32_e32 v206, s87, v236
	ds_read_b128 v[194:197], v206 offset:0
	ds_read_b128 v[198:201], v206 offset:0x2000
	s_waitcnt lgkmcnt(4)
	v_mfma_f32_32x32x16_bf16 v[2:17], v[174:177], v[190:193], v[2:17]
	ds_read_b64_tr_b16 v[190:191], v246 offset:0x3200
	ds_read_b64_tr_b16 v[192:193], v246 offset:0x3a00
	v_mfma_f32_32x32x16_bf16 v[2:17], v[170:173], v[186:189], v[2:17]
	ds_read_b64_tr_b16 v[186:187], v246 offset:0x2200
	ds_read_b64_tr_b16 v[188:189], v246 offset:0x2a00
	v_mfma_f32_32x32x16_bf16 v[2:17], v[166:169], v[182:185], v[2:17]
	ds_read_b64_tr_b16 v[182:183], v246 offset:0x1200
	ds_read_b64_tr_b16 v[184:185], v246 offset:0x1a00
	v_mfma_f32_32x32x16_bf16 v[2:17], v[162:165], v[178:181], v[2:17]
	ds_read_b64_tr_b16 v[178:179], v246 offset:0x200
	ds_read_b64_tr_b16 v[180:181], v246 offset:0xa00
	s_waitcnt lgkmcnt(10)
	v_mfma_f32_32x32x16_bf16 v[98:113], v[202:205], v[150:153], v[98:113]
	v_mfma_f32_32x32x16_bf16 v[82:97], v[250:253], v[150:153], v[82:97]
	ds_read_b128 v[202:205], v248 offset:0x80
	ds_read_b128 v[250:253], v248 offset:0x2080
	s_waitcnt lgkmcnt(10)
	v_mfma_f32_32x32x16_bf16 v[98:113], v[194:197], v[146:149], v[98:113]
	v_mfma_f32_32x32x16_bf16 v[82:97], v[198:201], v[146:149], v[82:97]
	ds_read_b128 v[194:197], v247 offset:0x80
	ds_read_b128 v[198:201], v247 offset:0x2080
	s_waitcnt lgkmcnt(4)
	v_mfma_f32_32x32x16_bf16 v[50:65], v[174:177], v[178:181], v[50:65]
	ds_read_b64_tr_b16 v[178:179], v246 offset:0x400
	ds_read_b64_tr_b16 v[180:181], v246 offset:0xc00
	v_mfma_f32_32x32x16_bf16 v[50:65], v[170:173], v[182:185], v[50:65]
	ds_read_b64_tr_b16 v[182:183], v246 offset:0x1400
	ds_read_b64_tr_b16 v[184:185], v246 offset:0x1c00
	v_mfma_f32_32x32x16_bf16 v[50:65], v[166:169], v[186:189], v[50:65]
	ds_read_b64_tr_b16 v[186:187], v246 offset:0x2400
	ds_read_b64_tr_b16 v[188:189], v246 offset:0x2c00
	v_mfma_f32_32x32x16_bf16 v[50:65], v[162:165], v[190:193], v[50:65]
	ds_read_b64_tr_b16 v[190:191], v246 offset:0x3400
	ds_read_b64_tr_b16 v[192:193], v246 offset:0x3c00
	s_waitcnt lgkmcnt(10)
	v_mfma_f32_32x32x16_bf16 v[98:113], v[202:205], v[142:145], v[98:113]
	v_mfma_f32_32x32x16_bf16 v[82:97], v[250:253], v[142:145], v[82:97]
	ds_read_b128 v[202:205], v217 offset:0x80
	ds_read_b128 v[248:251], v217 offset:0x2080
	s_waitcnt lgkmcnt(10)
	v_mfma_f32_32x32x16_bf16 v[98:113], v[194:197], v[138:141], v[98:113]
	v_mfma_f32_32x32x16_bf16 v[82:97], v[198:201], v[138:141], v[82:97]
	ds_read_b128 v[194:197], v206 offset:0x80
	ds_read_b128 v[198:201], v206 offset:0x2080
	s_waitcnt lgkmcnt(4)
	v_mfma_f32_32x32x16_bf16 v[34:49], v[174:177], v[178:181], v[34:49]
	ds_read_b64_tr_b16 v[178:179], v246 offset:0x600
	ds_read_b64_tr_b16 v[180:181], v246 offset:0xe00
	v_mfma_f32_32x32x16_bf16 v[34:49], v[170:173], v[182:185], v[34:49]
	ds_read_b64_tr_b16 v[182:183], v246 offset:0x1600
	ds_read_b64_tr_b16 v[184:185], v246 offset:0x1e00
	v_mfma_f32_32x32x16_bf16 v[34:49], v[166:169], v[186:189], v[34:49]
	ds_read_b64_tr_b16 v[186:187], v246 offset:0x2600
	ds_read_b64_tr_b16 v[188:189], v246 offset:0x2e00
	v_mfma_f32_32x32x16_bf16 v[34:49], v[162:165], v[190:193], v[34:49]
	ds_read_b64_tr_b16 v[190:191], v246 offset:0x3600
	ds_read_b64_tr_b16 v[192:193], v246 offset:0x3e00
	s_waitcnt lgkmcnt(10)
	v_mfma_f32_32x32x16_bf16 v[98:113], v[202:205], v[134:137], v[98:113]
	v_mfma_f32_32x32x16_bf16 v[82:97], v[248:251], v[134:137], v[82:97]
	s_waitcnt lgkmcnt(8)
	v_mfma_f32_32x32x16_bf16 v[98:113], v[194:197], v[130:133], v[98:113]
	v_mfma_f32_32x32x16_bf16 v[82:97], v[198:201], v[130:133], v[82:97]
	s_waitcnt lgkmcnt(0)
	v_mfma_f32_32x32x16_bf16 v[18:33], v[174:177], v[178:181], v[18:33]
	s_mov_b64 s[86:87], -1
	s_and_b64 vcc, exec, s[0:1]
	v_mfma_f32_32x32x16_bf16 v[18:33], v[170:173], v[182:185], v[18:33]
	v_mfma_f32_32x32x16_bf16 v[18:33], v[166:169], v[186:189], v[18:33]
	v_mfma_f32_32x32x16_bf16 v[18:33], v[162:165], v[190:193], v[18:33]
	s_cbranch_vccz .LBB0_72
	s_waitcnt lgkmcnt(0)
	s_barrier
	s_cbranch_execz .LBB0_73
